# out-proj-phase weight conversion: 8 loads per batch (loop kept) instead of 32
# speedup vs baseline: 1.0175x; 1.0090x over previous
; #define LAS __attribute__((address_space(3)))
; __device__ __forceinline__ unsigned pk2(float lo, float hi) { return pg8::cvt_pk_bf16(lo, hi); }
; __device__ __forceinline__ void transpose_item(const float* __restrict__ W, int K, int N, bf16* __restrict__ WT, int mode, LAS float* scr, int item, int lane) {
;     const int nblk = N / 32, kb = item / nblk, nb = item % nblk, k0 = 64 * kb, n0 = 32 * nb;
; #pragma unroll 8
;     for (int i = 0; i < 32; ++i) { const int kk = 2 * i + (lane >> 5); scr[kk * 33 + (lane & 31)] = __builtin_nontemporal_load(W + (size_t)(k0 + kk) * N + n0 + (lane & 31)); }
;     asm volatile("s_waitcnt lgkmcnt(0)" ::: "memory");
;     const int c = lane & 7; const int r0 = rowmap(mode, n0);
; #pragma unroll
;     for (int j = 0; j < 4; ++j) { const int n = (lane >> 3) + 8 * j; const LAS float* s = scr + (8 * c) * 33 + n;
;         u32x4 o; o.x = pk2(s[0 * 33], s[1 * 33]); o.y = pk2(s[2 * 33], s[3 * 33]); o.z = pk2(s[4 * 33], s[5 * 33]); o.w = pk2(s[6 * 33], s[7 * 33]);
;         *(u32x4*)(WT + (size_t)(r0 + n) * K + k0 + 8 * c) = o; }
;     asm volatile("s_waitcnt lgkmcnt(0)" ::: "memory");
; __device__ __forceinline__ void convert_weights(ArgP A, unsigned char* lds_g, int gw, int NGW, int l0, int l1, int lane, int wave) {
;     ...
;     for (int it = l0 * PER_L + gw; it < l1 * PER_L; it += NGW) {
;         const int l = it / PER_L; int r = it - l * PER_L;
;         if (r < I_IN) { transpose_item(A->w_in + (size_t)l * DM * INW, DM, INW, (bf16*)(ws + WS_WIN) + (size_t)l * INW * DM, 1, scr, r, lane); continue; } r -= I_IN;
;         if (r < I_OUT) { transpose_item(A->w_out + (size_t)l * DM * DM, DM, DM, (bf16*)(ws + WS_WOUT) + (size_t)l * DM * DM, 0, scr, r, lane); continue; } r -= I_OUT;
;         if (r < I_F1) { transpose_item(A->w_ffn_in + (size_t)l * DM * FF2, DM, FF2, (bf16*)(ws + WS_WF1) + (size_t)l * FF2 * DM, 2, scr, r, lane); continue; } r -= I_F1;
;         transpose_item(A->w_ffn_out + (size_t)l * FFH * DM, FFH, DM, (bf16*)(ws + WS_WF2) + (size_t)l * DM * FFH, 0, scr, r, lane);
;     }
.LBB0_193:
	v_add_u32_e32 v12, s7, v8
	v_add_u32_e32 v10, 0xffffdf00, v12
	v_ashrrev_i32_e32 v11, 31, v10
	v_lshlrev_b64 v[10:11], 12, v[10:11]
	v_lshl_add_u64 v[10:11], v[6:7], 0, v[10:11]
	global_load_dword v172, v[10:11], off nt
	v_add_u32_e32 v10, 0xffffdf02, v12
	v_ashrrev_i32_e32 v11, 31, v10
	v_lshlrev_b64 v[10:11], 12, v[10:11]
	v_lshl_add_u64 v[10:11], v[6:7], 0, v[10:11]
	global_load_dword v173, v[10:11], off nt
	s_add_i32 s7, s7, 16
	v_add_u32_e32 v10, 0xffffdf04, v12
	v_ashrrev_i32_e32 v11, 31, v10
	v_lshlrev_b64 v[10:11], 12, v[10:11]
	v_lshl_add_u64 v[10:11], v[6:7], 0, v[10:11]
	global_load_dword v174, v[10:11], off nt
	v_add_u32_e32 v10, 0xffffdf06, v12
	v_ashrrev_i32_e32 v11, 31, v10
	v_lshlrev_b64 v[10:11], 12, v[10:11]
	v_lshl_add_u64 v[10:11], v[6:7], 0, v[10:11]
	global_load_dword v175, v[10:11], off nt
	v_add_u32_e32 v10, 0xffffdf08, v12
	v_ashrrev_i32_e32 v11, 31, v10
	v_lshlrev_b64 v[10:11], 12, v[10:11]
	v_lshl_add_u64 v[10:11], v[6:7], 0, v[10:11]
	global_load_dword v176, v[10:11], off nt
	v_add_u32_e32 v10, 0xffffdf0a, v12
	v_ashrrev_i32_e32 v11, 31, v10
	v_lshlrev_b64 v[10:11], 12, v[10:11]
	v_lshl_add_u64 v[10:11], v[6:7], 0, v[10:11]
	global_load_dword v177, v[10:11], off nt
	v_add_u32_e32 v10, 0xffffdf0c, v12
	v_ashrrev_i32_e32 v11, 31, v10
	v_lshlrev_b64 v[10:11], 12, v[10:11]
	v_lshl_add_u64 v[10:11], v[6:7], 0, v[10:11]
	global_load_dword v178, v[10:11], off nt
	v_add_u32_e32 v10, 0xffffdf0e, v12
	v_ashrrev_i32_e32 v11, 31, v10
	v_lshlrev_b64 v[10:11], 12, v[10:11]
	v_lshl_add_u64 v[10:11], v[6:7], 0, v[10:11]
	global_load_dword v179, v[10:11], off nt
	s_cmp_lg_u32 s7, 64
	v_add_u32_e32 v14, 0x400, v9
	s_waitcnt vmcnt(6)
	ds_write2_b32 v9, v172, v173 offset1:66
	s_waitcnt vmcnt(4)
	ds_write2_b32 v9, v174, v175 offset0:132 offset1:198
	v_add_u32_e32 v9, 0x840, v9
	s_waitcnt vmcnt(2)
	ds_write2_b32 v14, v176, v177 offset0:8 offset1:74
	s_waitcnt vmcnt(0)
	ds_write2_b32 v14, v178, v179 offset0:140 offset1:206
	s_cbranch_scc1 .LBB0_193
	s_lshl_b32 s7, s8, 1
	s_waitcnt lgkmcnt(0)
	s_andn2_b32 s7, s7, 63
	ds_read2_b32 v[8:9], v22 offset1:33
	s_add_i32 s72, s7, 0xffffdf00
	s_mul_i32 s22, s4, 0x580000
	s_waitcnt lgkmcnt(0)
	v_cvt_pk_bf16_f32 v8, v8, v9
	ds_read2_b32 v[10:11], v22 offset0:66 offset1:99
	s_mul_hi_i32 s7, s4, 0x580000
	s_add_u32 s25, s11, s22
	s_waitcnt lgkmcnt(0)
	v_cvt_pk_bf16_f32 v9, v10, v11
	ds_read2_b32 v[10:11], v22 offset0:132 offset1:165
	s_addc_u32 s7, s13, s7
	s_lshl_b64 s[22:23], s[72:73], 1
	s_waitcnt lgkmcnt(0)
	v_cvt_pk_bf16_f32 v10, v10, v11
	ds_read2_b32 v[12:13], v22 offset0:198 offset1:231
	s_add_u32 s22, s25, s22
	s_waitcnt lgkmcnt(0)
	v_cvt_pk_bf16_f32 v11, v12, v13
	v_or_b32_e32 v12, s6, v3
	s_addc_u32 s23, s7, s23
	v_lshlrev_b32_e32 v160, 1, v2
	v_mul_u32_u24_e32 v12, 0xb00, v12
	v_lshl_add_u64 v[6:7], s[22:23], 0, v[160:161]
	v_lshlrev_b32_e32 v160, 1, v12
	v_lshl_add_u64 v[12:13], v[6:7], 0, v[160:161]
	global_store_dwordx4 v[12:13], v[8:11], off
	ds_read2_b32 v[8:9], v22 offset0:8 offset1:41
	s_waitcnt lgkmcnt(0)
	v_cvt_pk_bf16_f32 v8, v8, v9
	ds_read2_b32 v[10:11], v22 offset0:74 offset1:107
	s_waitcnt lgkmcnt(0)
	v_cvt_pk_bf16_f32 v9, v10, v11
	ds_read2_b32 v[10:11], v22 offset0:140 offset1:173
	s_waitcnt lgkmcnt(0)
	v_cvt_pk_bf16_f32 v10, v10, v11
	ds_read2_b32 v[12:13], v22 offset0:206 offset1:239
	s_waitcnt lgkmcnt(0)
	v_cvt_pk_bf16_f32 v11, v12, v13
	v_or_b32_e32 v12, s6, v23
	v_mul_u32_u24_e32 v12, 0xb00, v12
	v_lshlrev_b32_e32 v160, 1, v12
	v_lshl_add_u64 v[12:13], v[6:7], 0, v[160:161]
	global_store_dwordx4 v[12:13], v[8:11], off
	ds_read2_b32 v[8:9], v22 offset0:16 offset1:49
	s_waitcnt lgkmcnt(0)
	v_cvt_pk_bf16_f32 v8, v8, v9
	ds_read2_b32 v[10:11], v22 offset0:82 offset1:115
	s_waitcnt lgkmcnt(0)
	v_cvt_pk_bf16_f32 v9, v10, v11
	ds_read2_b32 v[10:11], v22 offset0:148 offset1:181
	s_waitcnt lgkmcnt(0)
	v_cvt_pk_bf16_f32 v10, v10, v11
	ds_read2_b32 v[12:13], v22 offset0:214 offset1:247
	s_waitcnt lgkmcnt(0)
	v_cvt_pk_bf16_f32 v11, v12, v13
	v_or_b32_e32 v12, s6, v24
	v_mul_u32_u24_e32 v12, 0xb00, v12
	v_lshlrev_b32_e32 v160, 1, v12
	v_lshl_add_u64 v[12:13], v[6:7], 0, v[160:161]
	global_store_dwordx4 v[12:13], v[8:11], off
	ds_read2_b32 v[8:9], v22 offset0:24 offset1:57
	s_waitcnt lgkmcnt(0)
	v_cvt_pk_bf16_f32 v8, v8, v9
	ds_read2_b32 v[10:11], v22 offset0:90 offset1:123
	s_waitcnt lgkmcnt(0)
	v_cvt_pk_bf16_f32 v9, v10, v11
	ds_read2_b32 v[10:11], v22 offset0:156 offset1:189
	s_waitcnt lgkmcnt(0)
	v_cvt_pk_bf16_f32 v10, v10, v11
	ds_read2_b32 v[12:13], v22 offset0:222 offset1:255
	s_waitcnt lgkmcnt(0)
	v_cvt_pk_bf16_f32 v11, v12, v13
	v_or_b32_e32 v12, s6, v25
	v_mul_u32_u24_e32 v12, 0xb00, v12
	v_lshlrev_b32_e32 v160, 1, v12
	v_lshl_add_u64 v[6:7], v[6:7], 0, v[160:161]
	global_store_dwordx4 v[6:7], v[8:11], off
	s_waitcnt lgkmcnt(0)
	s_mov_b64 s[6:7], 0

; #define LAS __attribute__((address_space(3)))
; __device__ __forceinline__ unsigned pk2(float lo, float hi) { return pg8::cvt_pk_bf16(lo, hi); }
; __device__ __forceinline__ void transpose_item(const float* __restrict__ W, int K, int N, bf16* __restrict__ WT, int mode, LAS float* scr, int item, int lane) {
;     const int nblk = N / 32, kb = item / nblk, nb = item % nblk, k0 = 64 * kb, n0 = 32 * nb;
; #pragma unroll 8
;     for (int i = 0; i < 32; ++i) { const int kk = 2 * i + (lane >> 5); scr[kk * 33 + (lane & 31)] = __builtin_nontemporal_load(W + (size_t)(k0 + kk) * N + n0 + (lane & 31)); }
;     asm volatile("s_waitcnt lgkmcnt(0)" ::: "memory");
;     const int c = lane & 7; const int r0 = rowmap(mode, n0);
; #pragma unroll
;     for (int j = 0; j < 4; ++j) { const int n = (lane >> 3) + 8 * j; const LAS float* s = scr + (8 * c) * 33 + n;
;         u32x4 o; o.x = pk2(s[0 * 33], s[1 * 33]); o.y = pk2(s[2 * 33], s[3 * 33]); o.z = pk2(s[4 * 33], s[5 * 33]); o.w = pk2(s[6 * 33], s[7 * 33]);
;         *(u32x4*)(WT + (size_t)(r0 + n) * K + k0 + 8 * c) = o; }
;     asm volatile("s_waitcnt lgkmcnt(0)" ::: "memory");
.LBB0_197:
	v_lshl_add_u64 v[36:37], v[20:21], 0, s[6:7]
	global_load_dword v172, v[36:37], off nt
	v_lshl_add_u64 v[36:37], v[18:19], 0, s[6:7]
	global_load_dword v173, v[36:37], off nt
	v_lshl_add_u64 v[36:37], v[16:17], 0, s[6:7]
	global_load_dword v174, v[36:37], off nt
	v_lshl_add_u64 v[36:37], v[14:15], 0, s[6:7]
	global_load_dword v175, v[36:37], off nt
	v_lshl_add_u64 v[36:37], v[12:13], 0, s[6:7]
	global_load_dword v176, v[36:37], off nt
	v_lshl_add_u64 v[36:37], v[10:11], 0, s[6:7]
	global_load_dword v177, v[36:37], off nt
	v_lshl_add_u64 v[36:37], v[8:9], 0, s[6:7]
	global_load_dword v178, v[36:37], off nt
	v_lshl_add_u64 v[36:37], v[6:7], 0, s[6:7]
	global_load_dword v179, v[36:37], off nt
	s_add_u32 s6, s6, 0x58000
	s_addc_u32 s7, s7, 0
	s_cmp_lg_u32 s6, 0x160000
	v_add_u32_e32 v38, 0x400, v34
	s_waitcnt vmcnt(6)
	ds_write2_b32 v34, v172, v173 offset1:66
	s_waitcnt vmcnt(4)
	ds_write2_b32 v34, v174, v175 offset0:132 offset1:198
	v_add_u32_e32 v34, 0x840, v34
	s_waitcnt vmcnt(2)
	ds_write2_b32 v38, v176, v177 offset0:8 offset1:74
	s_waitcnt vmcnt(0)
	ds_write2_b32 v38, v178, v179 offset0:140 offset1:206
	s_cbranch_scc1 .LBB0_197
	s_add_u32 s6, s14, s9
	s_addc_u32 s7, s15, s5
	s_and_b32 s5, 0xffff, s25
	s_and_b32 s9, 0xffff, s23
	s_cmpk_gt_u32 s9, 0x57
	s_cselect_b32 s9, 0xfffff500, 0
	s_waitcnt lgkmcnt(0)
	s_cselect_b32 s23, 0x80, 0
	s_add_i32 s9, s9, s5
	s_lshl_b32 s9, s9, 1
	s_and_b32 s5, s5, 0x60
	ds_read2_b32 v[8:9], v22 offset1:33
	s_and_b32 s9, s9, 0xffffff00
	s_or_b32 s5, s5, s23
	s_waitcnt lgkmcnt(0)
	v_cvt_pk_bf16_f32 v8, v8, v9
	ds_read2_b32 v[10:11], v22 offset0:66 offset1:99
	s_or_b32 s5, s5, s9
	s_and_b32 s9, 0xffff, s22
	s_waitcnt lgkmcnt(0)
	v_cvt_pk_bf16_f32 v9, v10, v11
	ds_read2_b32 v[10:11], v22 offset0:132 offset1:165
	s_lshl_b32 s9, s9, 1
	s_waitcnt lgkmcnt(0)
	v_cvt_pk_bf16_f32 v10, v10, v11
	ds_read2_b32 v[12:13], v22 offset0:198 offset1:231
	s_add_u32 s6, s6, s9
	s_waitcnt lgkmcnt(0)
	v_cvt_pk_bf16_f32 v11, v12, v13
	v_or_b32_e32 v12, s5, v3
	s_addc_u32 s7, s7, 0
	v_lshlrev_b32_e32 v160, 1, v2
	v_ashrrev_i32_e32 v13, 31, v12
	v_lshl_add_u64 v[6:7], s[6:7], 0, v[160:161]
	v_lshlrev_b64 v[12:13], 11, v[12:13]
	v_lshl_add_u64 v[12:13], v[6:7], 0, v[12:13]
	global_store_dwordx4 v[12:13], v[8:11], off
	ds_read2_b32 v[8:9], v22 offset0:8 offset1:41
	s_waitcnt lgkmcnt(0)
	v_cvt_pk_bf16_f32 v8, v8, v9
	ds_read2_b32 v[10:11], v22 offset0:74 offset1:107
	s_waitcnt lgkmcnt(0)
	v_cvt_pk_bf16_f32 v9, v10, v11
	ds_read2_b32 v[10:11], v22 offset0:140 offset1:173
	s_waitcnt lgkmcnt(0)
	v_cvt_pk_bf16_f32 v10, v10, v11
	ds_read2_b32 v[12:13], v22 offset0:206 offset1:239
	s_waitcnt lgkmcnt(0)
	v_cvt_pk_bf16_f32 v11, v12, v13
	v_or_b32_e32 v12, s5, v23
	v_ashrrev_i32_e32 v13, 31, v12
	v_lshlrev_b64 v[12:13], 11, v[12:13]
	v_lshl_add_u64 v[12:13], v[6:7], 0, v[12:13]
	global_store_dwordx4 v[12:13], v[8:11], off
	ds_read2_b32 v[8:9], v22 offset0:16 offset1:49
	s_waitcnt lgkmcnt(0)
	v_cvt_pk_bf16_f32 v8, v8, v9
	ds_read2_b32 v[10:11], v22 offset0:82 offset1:115
	s_waitcnt lgkmcnt(0)
	v_cvt_pk_bf16_f32 v9, v10, v11
	ds_read2_b32 v[10:11], v22 offset0:148 offset1:181
	s_waitcnt lgkmcnt(0)
	v_cvt_pk_bf16_f32 v10, v10, v11
	ds_read2_b32 v[12:13], v22 offset0:214 offset1:247
	s_waitcnt lgkmcnt(0)
	v_cvt_pk_bf16_f32 v11, v12, v13
	v_or_b32_e32 v12, s5, v24
	v_ashrrev_i32_e32 v13, 31, v12
	v_lshlrev_b64 v[12:13], 11, v[12:13]
	v_lshl_add_u64 v[12:13], v[6:7], 0, v[12:13]
	global_store_dwordx4 v[12:13], v[8:11], off
	ds_read2_b32 v[8:9], v22 offset0:24 offset1:57
	s_waitcnt lgkmcnt(0)
	v_cvt_pk_bf16_f32 v8, v8, v9
	ds_read2_b32 v[10:11], v22 offset0:90 offset1:123
	s_waitcnt lgkmcnt(0)
	v_cvt_pk_bf16_f32 v9, v10, v11
	ds_read2_b32 v[10:11], v22 offset0:156 offset1:189
	s_waitcnt lgkmcnt(0)
	v_cvt_pk_bf16_f32 v10, v10, v11
	ds_read2_b32 v[12:13], v22 offset0:222 offset1:255
	s_waitcnt lgkmcnt(0)
	v_cvt_pk_bf16_f32 v11, v12, v13
	v_or_b32_e32 v12, s5, v25
	v_ashrrev_i32_e32 v13, 31, v12
	v_lshlrev_b64 v[12:13], 11, v[12:13]
	v_lshl_add_u64 v[6:7], v[6:7], 0, v[12:13]
	global_store_dwordx4 v[6:7], v[8:11], off
	s_waitcnt lgkmcnt(0)

; #define LAS __attribute__((address_space(3)))
; __device__ __forceinline__ unsigned pk2(float lo, float hi) { return pg8::cvt_pk_bf16(lo, hi); }
; __device__ __forceinline__ void transpose_item(const float* __restrict__ W, int K, int N, bf16* __restrict__ WT, int mode, LAS float* scr, int item, int lane) {
;     const int nblk = N / 32, kb = item / nblk, nb = item % nblk, k0 = 64 * kb, n0 = 32 * nb;
; #pragma unroll 8
;     for (int i = 0; i < 32; ++i) { const int kk = 2 * i + (lane >> 5); scr[kk * 33 + (lane & 31)] = __builtin_nontemporal_load(W + (size_t)(k0 + kk) * N + n0 + (lane & 31)); }
;     asm volatile("s_waitcnt lgkmcnt(0)" ::: "memory");
;     const int c = lane & 7; const int r0 = rowmap(mode, n0);
; #pragma unroll
;     for (int j = 0; j < 4; ++j) { const int n = (lane >> 3) + 8 * j; const LAS float* s = scr + (8 * c) * 33 + n;
;         u32x4 o; o.x = pk2(s[0 * 33], s[1 * 33]); o.y = pk2(s[2 * 33], s[3 * 33]); o.z = pk2(s[4 * 33], s[5 * 33]); o.w = pk2(s[6 * 33], s[7 * 33]);
;         *(u32x4*)(WT + (size_t)(r0 + n) * K + k0 + 8 * c) = o; }
;     asm volatile("s_waitcnt lgkmcnt(0)" ::: "memory");
.LBB0_202:
	v_lshl_add_u64 v[36:37], v[20:21], 0, s[6:7]
	global_load_dword v172, v[36:37], off nt
	v_lshl_add_u64 v[36:37], v[18:19], 0, s[6:7]
	global_load_dword v173, v[36:37], off nt
	v_lshl_add_u64 v[36:37], v[16:17], 0, s[6:7]
	global_load_dword v174, v[36:37], off nt
	v_lshl_add_u64 v[36:37], v[14:15], 0, s[6:7]
	global_load_dword v175, v[36:37], off nt
	v_lshl_add_u64 v[36:37], v[12:13], 0, s[6:7]
	global_load_dword v176, v[36:37], off nt
	v_lshl_add_u64 v[36:37], v[10:11], 0, s[6:7]
	global_load_dword v177, v[36:37], off nt
	v_lshl_add_u64 v[36:37], v[8:9], 0, s[6:7]
	global_load_dword v178, v[36:37], off nt
	v_lshl_add_u64 v[36:37], v[6:7], 0, s[6:7]
	global_load_dword v179, v[36:37], off nt
	s_add_u32 s6, s6, 0x10000
	s_addc_u32 s7, s7, 0
	s_cmp_lg_u32 s6, 0x40000
	v_add_u32_e32 v38, 0x400, v34
	s_waitcnt vmcnt(6)
	ds_write2_b32 v34, v172, v173 offset1:66
	s_waitcnt vmcnt(4)
	ds_write2_b32 v34, v174, v175 offset0:132 offset1:198
	v_add_u32_e32 v34, 0x840, v34
	s_waitcnt vmcnt(2)
	ds_write2_b32 v38, v176, v177 offset0:8 offset1:74
	s_waitcnt vmcnt(0)
	ds_write2_b32 v38, v178, v179 offset0:140 offset1:206
	s_cbranch_scc1 .LBB0_202
	s_lshl_b32 s6, s8, 1
	s_add_i32 s6, s6, 0x1f900
	s_and_b32 s7, s6, 0x1ffc0
	s_lshl_b32 s6, s3, 5
	s_waitcnt lgkmcnt(0)
	s_and_b32 s6, s6, 0x3e0
	s_lshl_b64 s[22:23], s[4:5], 21
	ds_read2_b32 v[8:9], v22 offset1:33
	s_add_u32 s5, s16, s22
	s_waitcnt lgkmcnt(0)
	v_cvt_pk_bf16_f32 v8, v8, v9
	ds_read2_b32 v[10:11], v22 offset0:66 offset1:99
	s_addc_u32 s9, s17, s23
	s_lshl_b32 s7, s7, 1
	s_waitcnt lgkmcnt(0)
	v_cvt_pk_bf16_f32 v9, v10, v11
	ds_read2_b32 v[10:11], v22 offset0:132 offset1:165
	s_add_u32 s22, s5, s7
	s_waitcnt lgkmcnt(0)
	v_cvt_pk_bf16_f32 v10, v10, v11
	ds_read2_b32 v[12:13], v22 offset0:198 offset1:231
	s_addc_u32 s23, s9, 0
	v_lshlrev_b32_e32 v160, 1, v2
	s_waitcnt lgkmcnt(0)
	v_cvt_pk_bf16_f32 v11, v12, v13
	v_or_b32_e32 v12, s6, v3
	v_lshl_add_u64 v[6:7], s[22:23], 0, v[160:161]
	v_lshlrev_b32_e32 v160, 11, v12
	v_lshl_add_u64 v[12:13], v[6:7], 0, v[160:161]
	global_store_dwordx4 v[12:13], v[8:11], off
	ds_read2_b32 v[8:9], v22 offset0:8 offset1:41
	s_waitcnt lgkmcnt(0)
	v_cvt_pk_bf16_f32 v8, v8, v9
	ds_read2_b32 v[10:11], v22 offset0:74 offset1:107
	s_waitcnt lgkmcnt(0)
	v_cvt_pk_bf16_f32 v9, v10, v11
	ds_read2_b32 v[10:11], v22 offset0:140 offset1:173
	s_waitcnt lgkmcnt(0)
	v_cvt_pk_bf16_f32 v10, v10, v11
	ds_read2_b32 v[12:13], v22 offset0:206 offset1:239
	s_waitcnt lgkmcnt(0)
	v_cvt_pk_bf16_f32 v11, v12, v13
	v_or_b32_e32 v12, s6, v23
	v_lshlrev_b32_e32 v160, 11, v12
	v_lshl_add_u64 v[12:13], v[6:7], 0, v[160:161]
	global_store_dwordx4 v[12:13], v[8:11], off
	ds_read2_b32 v[8:9], v22 offset0:16 offset1:49
	s_waitcnt lgkmcnt(0)
	v_cvt_pk_bf16_f32 v8, v8, v9
	ds_read2_b32 v[10:11], v22 offset0:82 offset1:115
	s_waitcnt lgkmcnt(0)
	v_cvt_pk_bf16_f32 v9, v10, v11
	ds_read2_b32 v[10:11], v22 offset0:148 offset1:181
	s_waitcnt lgkmcnt(0)
	v_cvt_pk_bf16_f32 v10, v10, v11
	ds_read2_b32 v[12:13], v22 offset0:214 offset1:247
	s_waitcnt lgkmcnt(0)
	v_cvt_pk_bf16_f32 v11, v12, v13
	v_or_b32_e32 v12, s6, v24
	v_lshlrev_b32_e32 v160, 11, v12
	v_lshl_add_u64 v[12:13], v[6:7], 0, v[160:161]
	global_store_dwordx4 v[12:13], v[8:11], off
	ds_read2_b32 v[8:9], v22 offset0:24 offset1:57
	s_waitcnt lgkmcnt(0)
	v_cvt_pk_bf16_f32 v8, v8, v9
	ds_read2_b32 v[10:11], v22 offset0:90 offset1:123
	s_waitcnt lgkmcnt(0)
	v_cvt_pk_bf16_f32 v9, v10, v11
	ds_read2_b32 v[10:11], v22 offset0:156 offset1:189
	s_waitcnt lgkmcnt(0)
	v_cvt_pk_bf16_f32 v10, v10, v11
	ds_read2_b32 v[12:13], v22 offset0:222 offset1:255
	s_waitcnt lgkmcnt(0)
	v_cvt_pk_bf16_f32 v11, v12, v13
	v_or_b32_e32 v12, s6, v25
	v_lshlrev_b32_e32 v160, 11, v12
	v_lshl_add_u64 v[6:7], v[6:7], 0, v[160:161]
	global_store_dwordx4 v[6:7], v[8:11], off
	s_waitcnt lgkmcnt(0)

; #define LAS __attribute__((address_space(3)))
; __device__ __forceinline__ unsigned pk2(float lo, float hi) { return pg8::cvt_pk_bf16(lo, hi); }
; __device__ __forceinline__ void transpose_item(const float* __restrict__ W, int K, int N, bf16* __restrict__ WT, int mode, LAS float* scr, int item, int lane) {
;     const int nblk = N / 32, kb = item / nblk, nb = item % nblk, k0 = 64 * kb, n0 = 32 * nb;
; #pragma unroll 8
;     for (int i = 0; i < 32; ++i) { const int kk = 2 * i + (lane >> 5); scr[kk * 33 + (lane & 31)] = __builtin_nontemporal_load(W + (size_t)(k0 + kk) * N + n0 + (lane & 31)); }
;     asm volatile("s_waitcnt lgkmcnt(0)" ::: "memory");
;     const int c = lane & 7; const int r0 = rowmap(mode, n0);
; #pragma unroll
;     for (int j = 0; j < 4; ++j) { const int n = (lane >> 3) + 8 * j; const LAS float* s = scr + (8 * c) * 33 + n;
;         u32x4 o; o.x = pk2(s[0 * 33], s[1 * 33]); o.y = pk2(s[2 * 33], s[3 * 33]); o.z = pk2(s[4 * 33], s[5 * 33]); o.w = pk2(s[6 * 33], s[7 * 33]);
;         *(u32x4*)(WT + (size_t)(r0 + n) * K + k0 + 8 * c) = o; }
;     asm volatile("s_waitcnt lgkmcnt(0)" ::: "memory");
; __device__ __forceinline__ void convert_weights(ArgP A, unsigned char* lds_g, int gw, int NGW, int l0, int l1, int lane, int wave) {
;     ...
;     for (int it = l0 * PER_L + gw; it < l1 * PER_L; it += NGW) {
;         const int l = it / PER_L; int r = it - l * PER_L;
;         if (r < I_IN) { transpose_item(A->w_in + (size_t)l * DM * INW, DM, INW, (bf16*)(ws + WS_WIN) + (size_t)l * INW * DM, 1, scr, r, lane); continue; } r -= I_IN;
;         if (r < I_OUT) { transpose_item(A->w_out + (size_t)l * DM * DM, DM, DM, (bf16*)(ws + WS_WOUT) + (size_t)l * DM * DM, 0, scr, r, lane); continue; } r -= I_OUT;
;         if (r < I_F1) { transpose_item(A->w_ffn_in + (size_t)l * DM * FF2, DM, FF2, (bf16*)(ws + WS_WF1) + (size_t)l * FF2 * DM, 2, scr, r, lane); continue; } r -= I_F1;
;         transpose_item(A->w_ffn_out + (size_t)l * FFH * DM, FFH, DM, (bf16*)(ws + WS_WF2) + (size_t)l * DM * FFH, 0, scr, r, lane);
.LBB0_207:
	v_add_u32_e32 v12, s7, v8
	v_mad_i64_i32 v[10:11], s[22:23], v12, s59, v[6:7]
	global_load_dword v172, v[10:11], off nt
	v_add_u32_e32 v10, 2, v12
	v_mad_i64_i32 v[10:11], s[22:23], v10, s59, v[6:7]
	global_load_dword v173, v[10:11], off nt
	s_add_i32 s7, s7, 16
	v_add_u32_e32 v10, 4, v12
	v_mad_i64_i32 v[10:11], s[22:23], v10, s59, v[6:7]
	global_load_dword v174, v[10:11], off nt
	v_add_u32_e32 v10, 6, v12
	v_mad_i64_i32 v[10:11], s[22:23], v10, s59, v[6:7]
	global_load_dword v175, v[10:11], off nt
	v_add_u32_e32 v10, 8, v12
	v_mad_i64_i32 v[10:11], s[22:23], v10, s59, v[6:7]
	global_load_dword v176, v[10:11], off nt
	v_add_u32_e32 v10, 10, v12
	v_mad_i64_i32 v[10:11], s[22:23], v10, s59, v[6:7]
	global_load_dword v177, v[10:11], off nt
	v_add_u32_e32 v10, 12, v12
	v_mad_i64_i32 v[10:11], s[22:23], v10, s59, v[6:7]
	global_load_dword v178, v[10:11], off nt
	v_add_u32_e32 v10, 14, v12
	v_mad_i64_i32 v[10:11], s[22:23], v10, s59, v[6:7]
	global_load_dword v179, v[10:11], off nt
	s_cmp_lg_u32 s7, 64
	v_add_u32_e32 v14, 0x400, v9
	s_waitcnt vmcnt(6)
	ds_write2_b32 v9, v172, v173 offset1:66
	s_waitcnt vmcnt(4)
	ds_write2_b32 v9, v174, v175 offset0:132 offset1:198
	v_add_u32_e32 v9, 0x840, v9
	s_waitcnt vmcnt(2)
	ds_write2_b32 v14, v176, v177 offset0:8 offset1:74
	s_waitcnt vmcnt(0)
	ds_write2_b32 v14, v178, v179 offset0:140 offset1:206
	s_cbranch_scc1 .LBB0_207
	s_mul_hi_i32 s7, s4, 0x380000
	s_mul_i32 s4, s4, 0x380000
	s_add_u32 s9, s28, s4
	s_addc_u32 s22, s29, s7
	s_waitcnt lgkmcnt(0)
	s_lshl_b32 s5, s5, 7
	s_and_b32 s4, s8, 0xffffff00
	s_and_b32 s5, s5, 0x80
	ds_read2_b32 v[8:9], v22 offset1:33
	s_or_b32 s4, s5, s4
	s_lshr_b32 s5, s8, 1
	s_waitcnt lgkmcnt(0)
	v_cvt_pk_bf16_f32 v8, v8, v9
	ds_read2_b32 v[10:11], v22 offset0:66 offset1:99
	s_and_b32 s5, s5, 0x60
	s_ashr_i32 s7, s6, 31
	s_waitcnt lgkmcnt(0)
	v_cvt_pk_bf16_f32 v9, v10, v11
	ds_read2_b32 v[10:11], v22 offset0:132 offset1:165
	s_or_b32 s4, s4, s5
	s_lshl_b64 s[6:7], s[6:7], 1
	s_waitcnt lgkmcnt(0)
	v_cvt_pk_bf16_f32 v10, v10, v11
	ds_read2_b32 v[12:13], v22 offset0:198 offset1:231
	s_add_u32 s6, s9, s6
	s_waitcnt lgkmcnt(0)
	v_cvt_pk_bf16_f32 v11, v12, v13
	v_or_b32_e32 v12, s4, v3
	s_addc_u32 s7, s22, s7
	v_lshlrev_b32_e32 v160, 1, v2
	v_ashrrev_i32_e32 v13, 31, v12
	v_lshl_add_u64 v[6:7], s[6:7], 0, v[160:161]
	v_lshlrev_b64 v[12:13], 11, v[12:13]
	v_lshl_add_u64 v[12:13], v[6:7], 0, v[12:13]
	global_store_dwordx4 v[12:13], v[8:11], off
	ds_read2_b32 v[8:9], v22 offset0:8 offset1:41
	s_waitcnt lgkmcnt(0)
	v_cvt_pk_bf16_f32 v8, v8, v9
	ds_read2_b32 v[10:11], v22 offset0:74 offset1:107
	s_waitcnt lgkmcnt(0)
	v_cvt_pk_bf16_f32 v9, v10, v11
	ds_read2_b32 v[10:11], v22 offset0:140 offset1:173
	s_waitcnt lgkmcnt(0)
	v_cvt_pk_bf16_f32 v10, v10, v11
	ds_read2_b32 v[12:13], v22 offset0:206 offset1:239
	s_waitcnt lgkmcnt(0)
	v_cvt_pk_bf16_f32 v11, v12, v13
	v_or_b32_e32 v12, s4, v23
	v_ashrrev_i32_e32 v13, 31, v12
	v_lshlrev_b64 v[12:13], 11, v[12:13]
	v_lshl_add_u64 v[12:13], v[6:7], 0, v[12:13]
	global_store_dwordx4 v[12:13], v[8:11], off
	ds_read2_b32 v[8:9], v22 offset0:16 offset1:49
	s_waitcnt lgkmcnt(0)
	v_cvt_pk_bf16_f32 v8, v8, v9
	ds_read2_b32 v[10:11], v22 offset0:82 offset1:115
	s_waitcnt lgkmcnt(0)
	v_cvt_pk_bf16_f32 v9, v10, v11
	ds_read2_b32 v[10:11], v22 offset0:148 offset1:181
	s_waitcnt lgkmcnt(0)
	v_cvt_pk_bf16_f32 v10, v10, v11
	ds_read2_b32 v[12:13], v22 offset0:214 offset1:247
	s_waitcnt lgkmcnt(0)
	v_cvt_pk_bf16_f32 v11, v12, v13
	v_or_b32_e32 v12, s4, v24
	v_ashrrev_i32_e32 v13, 31, v12
	v_lshlrev_b64 v[12:13], 11, v[12:13]
	v_lshl_add_u64 v[12:13], v[6:7], 0, v[12:13]
	global_store_dwordx4 v[12:13], v[8:11], off
	ds_read2_b32 v[8:9], v22 offset0:24 offset1:57
	s_waitcnt lgkmcnt(0)
	v_cvt_pk_bf16_f32 v8, v8, v9
	ds_read2_b32 v[10:11], v22 offset0:90 offset1:123
	s_waitcnt lgkmcnt(0)
	v_cvt_pk_bf16_f32 v9, v10, v11
	ds_read2_b32 v[10:11], v22 offset0:156 offset1:189
	s_waitcnt lgkmcnt(0)
	v_cvt_pk_bf16_f32 v10, v10, v11
	ds_read2_b32 v[12:13], v22 offset0:222 offset1:255
	s_waitcnt lgkmcnt(0)
	v_cvt_pk_bf16_f32 v11, v12, v13
	v_or_b32_e32 v12, s4, v25
	v_ashrrev_i32_e32 v13, 31, v12
	v_lshlrev_b64 v[12:13], 11, v[12:13]
	v_lshl_add_u64 v[6:7], v[6:7], 0, v[12:13]
	global_store_dwordx4 v[6:7], v[8:11], off
	s_waitcnt lgkmcnt(0)
	s_branch .LBB0_188
